# v18 + LDS-DMA balance in the P6 K loop too (P6 epilogue buffers moved off v228-v235 so the carried DMA address registers survive between units)
# speedup vs baseline: 1.0131x; 1.0013x over previous
.LBB0_988:
	s_add_u32 s38, s24, 0x1d35000
	s_mov_b64 s[40:41], 0x80
	s_addc_u32 s39, s25, 0
	v_lshl_add_u64 v[8:9], v[8:9], 0, s[40:41]
	s_add_i32 m0, s3, 0x18000
	s_waitcnt vmcnt(2)
	s_barrier
	global_load_lds_dwordx4 v[8:9], off
	v_lshl_add_u64 v[4:5], v[4:5], 0, s[40:41]
	s_add_i32 m0, s3, 0x1a000
	s_add_i32 s49, s3, 0x8000
	global_load_lds_dwordx4 v[4:5], off
	v_mov_b32_e32 v230, v6
	v_mov_b32_e32 v231, v7
	v_mov_b32_e32 v232, v10
	v_mov_b32_e32 v233, v11
	v_lshl_add_u64 v[4:5], v[6:7], 0, s[40:41]
	s_mov_b32 m0, s49
	s_add_i32 s50, s3, 0xa000
	global_load_lds_dwordx4 v[4:5], off
	v_lshl_add_u64 v[4:5], v[10:11], 0, s[40:41]
	s_mov_b32 m0, s50
	v_lshl_add_u64 v[2:3], v[2:3], 0, s[40:41]
	global_load_lds_dwordx4 v[4:5], off
	s_add_i32 m0, s3, 0x1c000
	v_lshl_add_u64 v[0:1], v[0:1], 0, s[40:41]
	global_load_lds_dwordx4 v[2:3], off
	s_add_i32 m0, s3, 0x1e000
	s_lshr_b32 s5, s5, 26
	global_load_lds_dwordx4 v[0:1], off
	s_add_i32 s5, s4, s5
	v_and_b32_e32 v0, 15, v12
	s_ashr_i32 s51, s5, 6
	v_readlane_b32 s5, v248, 17
	v_and_b32_e32 v3, 48, v12
	v_and_b32_e32 v4, 0xfffffc00, v13
	v_or_b32_e32 v148, s5, v0
	v_lshlrev_b32_e32 v2, 6, v148
	s_movk_i32 s5, 0x3c0
	v_and_or_b32 v2, v2, s5, v3
	v_add_u32_e32 v5, s89, v4
	v_lshl_or_b32 v0, v0, 6, v3
	v_lshl_add_u32 v3, s29, 12, v4
	v_lshlrev_b32_e32 v4, 2, v12
	v_ashrrev_i32_e32 v1, 1, v12
	v_and_b32_e32 v4, 32, v4
	v_and_b32_e32 v1, -8, v1
	v_bitop3_b32 v149, v0, v3, v4 bitop3:0xde
	v_readlane_b32 s6, v248, 18
	v_add_u32_e32 v0, v16, v14
	v_add_lshl_u32 v0, v0, v15, 1
	v_add_u32_e32 v150, s6, v1
	v_mov_b32_e32 v1, v131
	v_lshlrev_b32_e32 v6, 2, v148
	s_cmp_gt_i32 s4, 63
	v_lshl_add_u64 v[136:137], s[16:17], 0, v[0:1]
	v_add_u32_e32 v0, v19, v17
	v_and_b32_e32 v6, 32, v6
	s_waitcnt vmcnt(6)
	s_cselect_b64 s[4:5], -1, 0
	v_add_lshl_u32 v0, v0, v18, 1
	v_bitop3_b32 v2, v2, v5, v6 bitop3:0xde
	v_lshl_add_u64 v[138:139], s[16:17], 0, v[0:1]
	v_cndmask_b32_e64 v0, 0, 1, s[4:5]
	s_add_i32 s53, 0, 0x10000
	s_add_i32 s54, 0, 0x14000
	s_add_i32 s52, s51, -2
	v_cmp_gt_u32_e64 s[10:11], 16, v12
	v_mov_b64_e32 v[140:141], 0x200
	v_mov_b64_e32 v[142:143], 0x1ff
	v_add_u32_e32 v151, s53, v149
	v_add_u32_e32 v152, s54, v149
	v_add_u32_e32 v153, 0, v2
	v_cmp_ne_u32_e64 s[4:5], 1, v0
	s_mov_b32 s55, 0
	s_barrier
	s_branch .LBB0_991

.LBB0_1001:
	s_and_b64 vcc, exec, s[4:5]
	s_waitcnt lgkmcnt(0)
	s_cbranch_vccnz .Lzx1003
	s_add_u32 s44, s44, 0x80
	s_addc_u32 s45, s45, 0
	s_add_u32 s59, s46, 0x100
	s_addc_u32 s60, s47, 0
	s_mov_b32 s46, 0
	ds_read_b128 v[144:147], v151
	ds_read_b128 v[154:157], v151 offset:1024
	ds_read_b128 v[158:161], v151 offset:2048
	ds_read_b128 v[162:165], v151 offset:3072
	ds_read_b128 v[166:169], v152
	ds_read_b128 v[170:173], v152 offset:1024
	ds_read_b128 v[174:177], v152 offset:2048
	ds_read_b128 v[178:181], v152 offset:3072
	s_add_i32 s61, s46, 2
	s_add_u32 s62, s44, 0x80
	s_addc_u32 s47, s45, 0
	s_cmp_eq_u32 s52, s46
	s_cselect_b32 s46, s8, s62
	s_cselect_b32 s47, s9, s47
	s_cselect_b32 s63, s43, s60
	s_cselect_b32 s62, s42, s59
	v_lshl_add_u64 v[182:183], v[230:231], 0, s[40:41]
	s_mov_b32 m0, s49
	s_nop 0
	global_load_lds_dwordx4 v[182:183], off
	v_lshl_add_u64 v[182:183], v[232:233], 0, s[40:41]
	s_mov_b32 m0, s50
	s_nop 0
	global_load_lds_dwordx4 v[182:183], off
	v_lshl_add_u64 v[182:183], s[44:45], 0, v[136:137]
	s_add_i32 m0, s3, 0xc000
	ds_read_b128 v[186:189], v153
	ds_read_b128 v[190:193], v153 offset:1024
	ds_read_b128 v[194:197], v153 offset:2048
	ds_read_b128 v[198:201], v153 offset:3072
	ds_read_b128 v[202:205], v153 offset:4096
	ds_read_b128 v[206:209], v153 offset:5120
	ds_read_b128 v[210:213], v153 offset:6144
	ds_read_b128 v[214:217], v153 offset:7168
	global_load_lds_dwordx4 v[182:183], off
	v_lshl_add_u64 v[182:183], s[44:45], 0, v[138:139]
	s_add_i32 m0, s3, 0xe000
	s_nop 0
	global_load_lds_dwordx4 v[182:183], off
	s_waitcnt vmcnt(8)
	s_waitcnt lgkmcnt(0)
	s_barrier
	s_setprio 1
	s_waitcnt lgkmcnt(0)
	v_mfma_f32_16x16x32_bf16 v[124:127], v[144:147], v[186:189], 0
	v_mfma_f32_16x16x32_bf16 v[120:123], v[158:161], v[186:189], 0
	v_mfma_f32_16x16x32_bf16 v[108:111], v[144:147], v[194:197], 0
	v_mfma_f32_16x16x32_bf16 v[104:107], v[158:161], v[194:197], 0
	v_mfma_f32_16x16x32_bf16 v[92:95], v[144:147], v[202:205], 0
	v_mfma_f32_16x16x32_bf16 v[88:91], v[158:161], v[202:205], 0
	v_mfma_f32_16x16x32_bf16 v[76:79], v[144:147], v[210:213], 0
	v_mfma_f32_16x16x32_bf16 v[72:75], v[158:161], v[210:213], 0
	v_mfma_f32_16x16x32_bf16 v[124:127], v[154:157], v[190:193], v[124:127]
	v_mfma_f32_16x16x32_bf16 v[120:123], v[162:165], v[190:193], v[120:123]
	v_mfma_f32_16x16x32_bf16 v[108:111], v[154:157], v[198:201], v[108:111]
	v_mfma_f32_16x16x32_bf16 v[104:107], v[162:165], v[198:201], v[104:107]
	v_mfma_f32_16x16x32_bf16 v[92:95], v[154:157], v[206:209], v[92:95]
	v_mfma_f32_16x16x32_bf16 v[88:91], v[162:165], v[206:209], v[88:91]
	v_mfma_f32_16x16x32_bf16 v[76:79], v[154:157], v[214:217], v[76:79]
	v_mfma_f32_16x16x32_bf16 v[72:75], v[162:165], v[214:217], v[72:75]
	s_setprio 0
	s_setprio 1
	v_mfma_f32_16x16x32_bf16 v[116:119], v[166:169], v[186:189], 0
	v_mfma_f32_16x16x32_bf16 v[112:115], v[174:177], v[186:189], 0
	v_mfma_f32_16x16x32_bf16 v[100:103], v[166:169], v[194:197], 0
	v_mfma_f32_16x16x32_bf16 v[96:99], v[174:177], v[194:197], 0
	v_mfma_f32_16x16x32_bf16 v[84:87], v[166:169], v[202:205], 0
	v_mfma_f32_16x16x32_bf16 v[80:83], v[174:177], v[202:205], 0
	v_mfma_f32_16x16x32_bf16 v[68:71], v[166:169], v[210:213], 0
	v_mfma_f32_16x16x32_bf16 v[64:67], v[174:177], v[210:213], 0
	v_mfma_f32_16x16x32_bf16 v[116:119], v[170:173], v[190:193], v[116:119]
	v_mfma_f32_16x16x32_bf16 v[112:115], v[178:181], v[190:193], v[112:115]
	v_mfma_f32_16x16x32_bf16 v[100:103], v[170:173], v[198:201], v[100:103]
	v_mfma_f32_16x16x32_bf16 v[96:99], v[178:181], v[198:201], v[96:99]
	v_mfma_f32_16x16x32_bf16 v[84:87], v[170:173], v[206:209], v[84:87]
	v_mfma_f32_16x16x32_bf16 v[80:83], v[178:181], v[206:209], v[80:83]
	v_mfma_f32_16x16x32_bf16 v[68:71], v[170:173], v[214:217], v[68:71]
	v_mfma_f32_16x16x32_bf16 v[64:67], v[178:181], v[214:217], v[64:67]
	s_setprio 0
	s_barrier
	s_add_i32 s64, s53, s31
	v_lshl_add_u64 v[182:183], s[62:63], 0, v[130:131]
	s_mov_b32 m0, s64
	ds_read_b128 v[186:189], v153 offset:16384
	ds_read_b128 v[190:193], v153 offset:17408
	ds_read_b128 v[194:197], v153 offset:18432
	ds_read_b128 v[198:201], v153 offset:19456
	ds_read_b128 v[202:205], v153 offset:20480
	ds_read_b128 v[206:209], v153 offset:21504
	ds_read_b128 v[210:213], v153 offset:22528
	ds_read_b128 v[214:217], v153 offset:23552
	global_load_lds_dwordx4 v[182:183], off
	s_add_i32 m0, s64, 0x2000
	v_lshl_add_u64 v[224:225], s[62:63], 0, v[134:135]
	s_add_u32 s62, s62, s16
	s_addc_u32 s63, s63, s17
	s_add_i32 s64, s54, s31
	global_load_lds_dwordx4 v[224:225], off
	v_lshl_add_u64 v[226:227], s[62:63], 0, v[130:131]
	s_mov_b32 m0, s64
	v_lshl_add_u64 v[228:229], s[62:63], 0, v[134:135]
	global_load_lds_dwordx4 v[226:227], off
	s_add_i32 m0, s64, 0x2000
	v_lshl_add_u64 v[230:231], s[46:47], 0, v[128:129]
	global_load_lds_dwordx4 v[228:229], off
	v_lshl_add_u64 v[232:233], s[46:47], 0, v[132:133]
	s_waitcnt vmcnt(6)
	s_waitcnt lgkmcnt(0)
	s_barrier
	s_setprio 1
	s_waitcnt lgkmcnt(0)
	v_mfma_f32_16x16x32_bf16 v[60:63], v[144:147], v[186:189], 0
	v_mfma_f32_16x16x32_bf16 v[56:59], v[158:161], v[186:189], 0
	v_mfma_f32_16x16x32_bf16 v[44:47], v[144:147], v[194:197], 0
	v_mfma_f32_16x16x32_bf16 v[40:43], v[158:161], v[194:197], 0
	v_mfma_f32_16x16x32_bf16 v[28:31], v[144:147], v[202:205], 0
	v_mfma_f32_16x16x32_bf16 v[24:27], v[158:161], v[202:205], 0
	v_mfma_f32_16x16x32_bf16 v[12:15], v[144:147], v[210:213], 0
	v_mfma_f32_16x16x32_bf16 v[8:11], v[158:161], v[210:213], 0
	v_mfma_f32_16x16x32_bf16 v[60:63], v[154:157], v[190:193], v[60:63]
	v_mfma_f32_16x16x32_bf16 v[56:59], v[162:165], v[190:193], v[56:59]
	v_mfma_f32_16x16x32_bf16 v[44:47], v[154:157], v[198:201], v[44:47]
	v_mfma_f32_16x16x32_bf16 v[40:43], v[162:165], v[198:201], v[40:43]
	v_mfma_f32_16x16x32_bf16 v[28:31], v[154:157], v[206:209], v[28:31]
	v_mfma_f32_16x16x32_bf16 v[24:27], v[162:165], v[206:209], v[24:27]
	v_mfma_f32_16x16x32_bf16 v[12:15], v[154:157], v[214:217], v[12:15]
	v_mfma_f32_16x16x32_bf16 v[8:11], v[162:165], v[214:217], v[8:11]
	s_setprio 0
	s_setprio 1
	v_mfma_f32_16x16x32_bf16 v[52:55], v[166:169], v[186:189], 0
	v_mfma_f32_16x16x32_bf16 v[48:51], v[174:177], v[186:189], 0
	v_mfma_f32_16x16x32_bf16 v[36:39], v[166:169], v[194:197], 0
	v_mfma_f32_16x16x32_bf16 v[32:35], v[174:177], v[194:197], 0
	v_mfma_f32_16x16x32_bf16 v[20:23], v[166:169], v[202:205], 0
	v_mfma_f32_16x16x32_bf16 v[16:19], v[174:177], v[202:205], 0
	v_mfma_f32_16x16x32_bf16 v[4:7], v[166:169], v[210:213], 0
	v_mfma_f32_16x16x32_bf16 v[0:3], v[174:177], v[210:213], 0
	v_mfma_f32_16x16x32_bf16 v[52:55], v[170:173], v[190:193], v[52:55]
	v_mfma_f32_16x16x32_bf16 v[48:51], v[178:181], v[190:193], v[48:51]
	v_mfma_f32_16x16x32_bf16 v[36:39], v[170:173], v[198:201], v[36:39]
	v_mfma_f32_16x16x32_bf16 v[32:35], v[178:181], v[198:201], v[32:35]
	v_mfma_f32_16x16x32_bf16 v[20:23], v[170:173], v[206:209], v[20:23]
	v_mfma_f32_16x16x32_bf16 v[16:19], v[178:181], v[206:209], v[16:19]
	v_mfma_f32_16x16x32_bf16 v[4:7], v[170:173], v[214:217], v[4:7]
	v_mfma_f32_16x16x32_bf16 v[0:3], v[178:181], v[214:217], v[0:3]
	s_setprio 0
	s_barrier
	s_add_i32 s62, 0, 0x18000
	s_add_i32 s63, 0, 0x1c000
	v_add_u32_e32 v162, s62, v149
	v_add_u32_e32 v178, s63, v149
	ds_read_b128 v[144:147], v162
	ds_read_b128 v[154:157], v162 offset:1024
	ds_read_b128 v[158:161], v162 offset:2048
	ds_read_b128 v[162:165], v162 offset:3072
	ds_read_b128 v[166:169], v178
	ds_read_b128 v[170:173], v178 offset:1024
	ds_read_b128 v[174:177], v178 offset:2048
	ds_read_b128 v[178:181], v178 offset:3072
	s_add_u32 s46, s46, s16
	s_addc_u32 s47, s47, s17
	s_mov_b32 m0, s3
	s_nop 0
	global_load_lds_dwordx4 v[230:231], off
	s_mov_b32 m0, s28
	s_nop 0
	global_load_lds_dwordx4 v[232:233], off
	s_mov_b32 m0, s33
	v_lshl_add_u64 v[234:235], s[46:47], 0, v[128:129]
	ds_read_b128 v[186:189], v153 offset:32768
	ds_read_b128 v[190:193], v153 offset:33792
	ds_read_b128 v[194:197], v153 offset:34816
	ds_read_b128 v[198:201], v153 offset:35840
	ds_read_b128 v[202:205], v153 offset:36864
	ds_read_b128 v[206:209], v153 offset:37888
	ds_read_b128 v[210:213], v153 offset:38912
	ds_read_b128 v[214:217], v153 offset:39936
	global_load_lds_dwordx4 v[234:235], off
	v_lshl_add_u64 v[234:235], s[46:47], 0, v[132:133]
	s_mov_b32 m0, s48
	s_nop 0
	global_load_lds_dwordx4 v[234:235], off
	s_waitcnt vmcnt(8)
	s_waitcnt lgkmcnt(0)
	s_barrier
	s_setprio 1
	s_waitcnt lgkmcnt(0)
	v_mfma_f32_16x16x32_bf16 v[124:127], v[144:147], v[186:189], v[124:127]
	v_mfma_f32_16x16x32_bf16 v[120:123], v[158:161], v[186:189], v[120:123]
	v_mfma_f32_16x16x32_bf16 v[108:111], v[144:147], v[194:197], v[108:111]
	v_mfma_f32_16x16x32_bf16 v[104:107], v[158:161], v[194:197], v[104:107]
	v_mfma_f32_16x16x32_bf16 v[92:95], v[144:147], v[202:205], v[92:95]
	v_mfma_f32_16x16x32_bf16 v[88:91], v[158:161], v[202:205], v[88:91]
	v_mfma_f32_16x16x32_bf16 v[76:79], v[144:147], v[210:213], v[76:79]
	v_mfma_f32_16x16x32_bf16 v[72:75], v[158:161], v[210:213], v[72:75]
	v_mfma_f32_16x16x32_bf16 v[124:127], v[154:157], v[190:193], v[124:127]
	v_mfma_f32_16x16x32_bf16 v[120:123], v[162:165], v[190:193], v[120:123]
	v_mfma_f32_16x16x32_bf16 v[108:111], v[154:157], v[198:201], v[108:111]
	v_mfma_f32_16x16x32_bf16 v[104:107], v[162:165], v[198:201], v[104:107]
	v_mfma_f32_16x16x32_bf16 v[92:95], v[154:157], v[206:209], v[92:95]
	v_mfma_f32_16x16x32_bf16 v[88:91], v[162:165], v[206:209], v[88:91]
	v_mfma_f32_16x16x32_bf16 v[76:79], v[154:157], v[214:217], v[76:79]
	v_mfma_f32_16x16x32_bf16 v[72:75], v[162:165], v[214:217], v[72:75]
	s_setprio 0
	s_setprio 1
	v_mfma_f32_16x16x32_bf16 v[116:119], v[166:169], v[186:189], v[116:119]
	v_mfma_f32_16x16x32_bf16 v[112:115], v[174:177], v[186:189], v[112:115]
	v_mfma_f32_16x16x32_bf16 v[100:103], v[166:169], v[194:197], v[100:103]
	v_mfma_f32_16x16x32_bf16 v[96:99], v[174:177], v[194:197], v[96:99]
	v_mfma_f32_16x16x32_bf16 v[84:87], v[166:169], v[202:205], v[84:87]
	v_mfma_f32_16x16x32_bf16 v[80:83], v[174:177], v[202:205], v[80:83]
	v_mfma_f32_16x16x32_bf16 v[68:71], v[166:169], v[210:213], v[68:71]
	v_mfma_f32_16x16x32_bf16 v[64:67], v[174:177], v[210:213], v[64:67]
	v_mfma_f32_16x16x32_bf16 v[116:119], v[170:173], v[190:193], v[116:119]
	v_mfma_f32_16x16x32_bf16 v[112:115], v[178:181], v[190:193], v[112:115]
	v_mfma_f32_16x16x32_bf16 v[100:103], v[170:173], v[198:201], v[100:103]
	v_mfma_f32_16x16x32_bf16 v[96:99], v[178:181], v[198:201], v[96:99]
	v_mfma_f32_16x16x32_bf16 v[84:87], v[170:173], v[206:209], v[84:87]
	v_mfma_f32_16x16x32_bf16 v[80:83], v[178:181], v[206:209], v[80:83]
	v_mfma_f32_16x16x32_bf16 v[68:71], v[170:173], v[214:217], v[68:71]
	v_mfma_f32_16x16x32_bf16 v[64:67], v[178:181], v[214:217], v[64:67]
	s_setprio 0
	s_barrier
	s_add_i32 s46, s62, s31
	v_lshl_add_u64 v[182:183], v[182:183], 0, s[40:41]
	s_mov_b32 m0, s46
	ds_read_b128 v[186:189], v153 offset:49152
	ds_read_b128 v[190:193], v153 offset:50176
	ds_read_b128 v[194:197], v153 offset:51200
	ds_read_b128 v[198:201], v153 offset:52224
	ds_read_b128 v[202:205], v153 offset:53248
	ds_read_b128 v[206:209], v153 offset:54272
	ds_read_b128 v[210:213], v153 offset:55296
	ds_read_b128 v[214:217], v153 offset:56320
	global_load_lds_dwordx4 v[182:183], off
	v_lshl_add_u64 v[182:183], v[224:225], 0, s[40:41]
	s_add_i32 m0, s46, 0x2000
	s_add_i32 s46, s63, s31
	global_load_lds_dwordx4 v[182:183], off
	v_lshl_add_u64 v[182:183], v[226:227], 0, s[40:41]
	s_mov_b32 m0, s46
	s_nop 0
	global_load_lds_dwordx4 v[182:183], off
	v_lshl_add_u64 v[182:183], v[228:229], 0, s[40:41]
	s_add_i32 m0, s46, 0x2000
	s_nop 0
	global_load_lds_dwordx4 v[182:183], off
	s_waitcnt vmcnt(6)
	s_waitcnt lgkmcnt(0)
	s_barrier
	s_setprio 1
	s_waitcnt lgkmcnt(0)
	v_mfma_f32_16x16x32_bf16 v[60:63], v[144:147], v[186:189], v[60:63]
	v_mfma_f32_16x16x32_bf16 v[56:59], v[158:161], v[186:189], v[56:59]
	v_mfma_f32_16x16x32_bf16 v[44:47], v[144:147], v[194:197], v[44:47]
	v_mfma_f32_16x16x32_bf16 v[40:43], v[158:161], v[194:197], v[40:43]
	v_mfma_f32_16x16x32_bf16 v[28:31], v[144:147], v[202:205], v[28:31]
	v_mfma_f32_16x16x32_bf16 v[24:27], v[158:161], v[202:205], v[24:27]
	v_mfma_f32_16x16x32_bf16 v[12:15], v[144:147], v[210:213], v[12:15]
	v_mfma_f32_16x16x32_bf16 v[8:11], v[158:161], v[210:213], v[8:11]
	v_mfma_f32_16x16x32_bf16 v[60:63], v[154:157], v[190:193], v[60:63]
	v_mfma_f32_16x16x32_bf16 v[56:59], v[162:165], v[190:193], v[56:59]
	v_mfma_f32_16x16x32_bf16 v[44:47], v[154:157], v[198:201], v[44:47]
	v_mfma_f32_16x16x32_bf16 v[40:43], v[162:165], v[198:201], v[40:43]
	v_mfma_f32_16x16x32_bf16 v[28:31], v[154:157], v[206:209], v[28:31]
	v_mfma_f32_16x16x32_bf16 v[24:27], v[162:165], v[206:209], v[24:27]
	v_mfma_f32_16x16x32_bf16 v[12:15], v[154:157], v[214:217], v[12:15]
	v_mfma_f32_16x16x32_bf16 v[8:11], v[162:165], v[214:217], v[8:11]
	s_setprio 0
	s_setprio 1
	v_mfma_f32_16x16x32_bf16 v[52:55], v[166:169], v[186:189], v[52:55]
	v_mfma_f32_16x16x32_bf16 v[48:51], v[174:177], v[186:189], v[48:51]
	v_mfma_f32_16x16x32_bf16 v[36:39], v[166:169], v[194:197], v[36:39]
	v_mfma_f32_16x16x32_bf16 v[32:35], v[174:177], v[194:197], v[32:35]
	v_mfma_f32_16x16x32_bf16 v[20:23], v[166:169], v[202:205], v[20:23]
	v_mfma_f32_16x16x32_bf16 v[16:19], v[174:177], v[202:205], v[16:19]
	v_mfma_f32_16x16x32_bf16 v[4:7], v[166:169], v[210:213], v[4:7]
	v_mfma_f32_16x16x32_bf16 v[0:3], v[174:177], v[210:213], v[0:3]
	v_mfma_f32_16x16x32_bf16 v[52:55], v[170:173], v[190:193], v[52:55]
	v_mfma_f32_16x16x32_bf16 v[48:51], v[178:181], v[190:193], v[48:51]
	v_mfma_f32_16x16x32_bf16 v[36:39], v[170:173], v[198:201], v[36:39]
	v_mfma_f32_16x16x32_bf16 v[32:35], v[178:181], v[198:201], v[32:35]
	v_mfma_f32_16x16x32_bf16 v[20:23], v[170:173], v[206:209], v[20:23]
	v_mfma_f32_16x16x32_bf16 v[16:19], v[178:181], v[206:209], v[16:19]
	v_mfma_f32_16x16x32_bf16 v[4:7], v[170:173], v[214:217], v[4:7]
	v_mfma_f32_16x16x32_bf16 v[0:3], v[178:181], v[214:217], v[0:3]
	s_setprio 0
	s_barrier
	s_add_u32 s44, s44, 0x100
	s_addc_u32 s45, s45, 0
	s_add_u32 s59, s59, 0x100
	s_addc_u32 s60, s60, 0
	s_cmp_ge_i32 s61, s51
	s_mov_b32 s46, s61
	s_cbranch_scc1 .LBB0_1004
.LBB0_1003:
	ds_read_b128 v[144:147], v151
	ds_read_b128 v[154:157], v151 offset:1024
	ds_read_b128 v[158:161], v151 offset:2048
	ds_read_b128 v[162:165], v151 offset:3072
	ds_read_b128 v[166:169], v152
	ds_read_b128 v[170:173], v152 offset:1024
	ds_read_b128 v[174:177], v152 offset:2048
	ds_read_b128 v[178:181], v152 offset:3072
	s_add_i32 s61, s46, 2
	s_add_u32 s62, s44, 0x80
	s_addc_u32 s47, s45, 0
	s_cmp_eq_u32 s52, s46
	s_cselect_b32 s46, s8, s62
	s_cselect_b32 s47, s9, s47
	s_cselect_b32 s63, s43, s60
	s_cselect_b32 s62, s42, s59
	v_lshl_add_u64 v[182:183], v[230:231], 0, s[40:41]
	s_mov_b32 m0, s49
	s_nop 0
	global_load_lds_dwordx4 v[182:183], off
	v_lshl_add_u64 v[182:183], v[232:233], 0, s[40:41]
	s_mov_b32 m0, s50
	s_nop 0
	global_load_lds_dwordx4 v[182:183], off
	v_lshl_add_u64 v[182:183], s[44:45], 0, v[136:137]
	s_add_i32 m0, s3, 0xc000
	ds_read_b128 v[186:189], v153
	ds_read_b128 v[190:193], v153 offset:1024
	ds_read_b128 v[194:197], v153 offset:2048
	ds_read_b128 v[198:201], v153 offset:3072
	ds_read_b128 v[202:205], v153 offset:4096
	ds_read_b128 v[206:209], v153 offset:5120
	ds_read_b128 v[210:213], v153 offset:6144
	ds_read_b128 v[214:217], v153 offset:7168
	global_load_lds_dwordx4 v[182:183], off
	v_lshl_add_u64 v[182:183], s[44:45], 0, v[138:139]
	s_add_i32 m0, s3, 0xe000
	s_nop 0
	global_load_lds_dwordx4 v[182:183], off
	s_waitcnt vmcnt(8)
	s_waitcnt lgkmcnt(0)
	s_barrier
	s_setprio 1
	s_waitcnt lgkmcnt(0)
	v_mfma_f32_16x16x32_bf16 v[124:127], v[144:147], v[186:189], v[124:127]
	v_mfma_f32_16x16x32_bf16 v[120:123], v[158:161], v[186:189], v[120:123]
	v_mfma_f32_16x16x32_bf16 v[108:111], v[144:147], v[194:197], v[108:111]
	v_mfma_f32_16x16x32_bf16 v[104:107], v[158:161], v[194:197], v[104:107]
	v_mfma_f32_16x16x32_bf16 v[92:95], v[144:147], v[202:205], v[92:95]
	v_mfma_f32_16x16x32_bf16 v[88:91], v[158:161], v[202:205], v[88:91]
	v_mfma_f32_16x16x32_bf16 v[76:79], v[144:147], v[210:213], v[76:79]
	v_mfma_f32_16x16x32_bf16 v[72:75], v[158:161], v[210:213], v[72:75]
	v_mfma_f32_16x16x32_bf16 v[124:127], v[154:157], v[190:193], v[124:127]
	v_mfma_f32_16x16x32_bf16 v[120:123], v[162:165], v[190:193], v[120:123]
	v_mfma_f32_16x16x32_bf16 v[108:111], v[154:157], v[198:201], v[108:111]
	v_mfma_f32_16x16x32_bf16 v[104:107], v[162:165], v[198:201], v[104:107]
	v_mfma_f32_16x16x32_bf16 v[92:95], v[154:157], v[206:209], v[92:95]
	v_mfma_f32_16x16x32_bf16 v[88:91], v[162:165], v[206:209], v[88:91]
	v_mfma_f32_16x16x32_bf16 v[76:79], v[154:157], v[214:217], v[76:79]
	v_mfma_f32_16x16x32_bf16 v[72:75], v[162:165], v[214:217], v[72:75]
	s_setprio 0
	s_setprio 1
	v_mfma_f32_16x16x32_bf16 v[116:119], v[166:169], v[186:189], v[116:119]
	v_mfma_f32_16x16x32_bf16 v[112:115], v[174:177], v[186:189], v[112:115]
	v_mfma_f32_16x16x32_bf16 v[100:103], v[166:169], v[194:197], v[100:103]
	v_mfma_f32_16x16x32_bf16 v[96:99], v[174:177], v[194:197], v[96:99]
	v_mfma_f32_16x16x32_bf16 v[84:87], v[166:169], v[202:205], v[84:87]
	v_mfma_f32_16x16x32_bf16 v[80:83], v[174:177], v[202:205], v[80:83]
	v_mfma_f32_16x16x32_bf16 v[68:71], v[166:169], v[210:213], v[68:71]
	v_mfma_f32_16x16x32_bf16 v[64:67], v[174:177], v[210:213], v[64:67]
	v_mfma_f32_16x16x32_bf16 v[116:119], v[170:173], v[190:193], v[116:119]
	v_mfma_f32_16x16x32_bf16 v[112:115], v[178:181], v[190:193], v[112:115]
	v_mfma_f32_16x16x32_bf16 v[100:103], v[170:173], v[198:201], v[100:103]
	v_mfma_f32_16x16x32_bf16 v[96:99], v[178:181], v[198:201], v[96:99]
	v_mfma_f32_16x16x32_bf16 v[84:87], v[170:173], v[206:209], v[84:87]
	v_mfma_f32_16x16x32_bf16 v[80:83], v[178:181], v[206:209], v[80:83]
	v_mfma_f32_16x16x32_bf16 v[68:71], v[170:173], v[214:217], v[68:71]
	v_mfma_f32_16x16x32_bf16 v[64:67], v[178:181], v[214:217], v[64:67]
	s_setprio 0
	s_barrier
	s_add_i32 s64, s53, s31
	v_lshl_add_u64 v[182:183], s[62:63], 0, v[130:131]
	s_mov_b32 m0, s64
	ds_read_b128 v[186:189], v153 offset:16384
	ds_read_b128 v[190:193], v153 offset:17408
	ds_read_b128 v[194:197], v153 offset:18432
	ds_read_b128 v[198:201], v153 offset:19456
	ds_read_b128 v[202:205], v153 offset:20480
	ds_read_b128 v[206:209], v153 offset:21504
	ds_read_b128 v[210:213], v153 offset:22528
	ds_read_b128 v[214:217], v153 offset:23552
	global_load_lds_dwordx4 v[182:183], off
	s_add_i32 m0, s64, 0x2000
	v_lshl_add_u64 v[224:225], s[62:63], 0, v[134:135]
	s_add_u32 s62, s62, s16
	s_addc_u32 s63, s63, s17
	s_add_i32 s64, s54, s31
	global_load_lds_dwordx4 v[224:225], off
	v_lshl_add_u64 v[226:227], s[62:63], 0, v[130:131]
	s_mov_b32 m0, s64
	v_lshl_add_u64 v[228:229], s[62:63], 0, v[134:135]
	global_load_lds_dwordx4 v[226:227], off
	s_add_i32 m0, s64, 0x2000
	v_lshl_add_u64 v[230:231], s[46:47], 0, v[128:129]
	global_load_lds_dwordx4 v[228:229], off
	v_lshl_add_u64 v[232:233], s[46:47], 0, v[132:133]
	s_waitcnt vmcnt(6)
	s_waitcnt lgkmcnt(0)
	s_barrier
	s_setprio 1
	s_waitcnt lgkmcnt(0)
	v_mfma_f32_16x16x32_bf16 v[60:63], v[144:147], v[186:189], v[60:63]
	v_mfma_f32_16x16x32_bf16 v[56:59], v[158:161], v[186:189], v[56:59]
	v_mfma_f32_16x16x32_bf16 v[44:47], v[144:147], v[194:197], v[44:47]
	v_mfma_f32_16x16x32_bf16 v[40:43], v[158:161], v[194:197], v[40:43]
	v_mfma_f32_16x16x32_bf16 v[28:31], v[144:147], v[202:205], v[28:31]
	v_mfma_f32_16x16x32_bf16 v[24:27], v[158:161], v[202:205], v[24:27]
	v_mfma_f32_16x16x32_bf16 v[12:15], v[144:147], v[210:213], v[12:15]
	v_mfma_f32_16x16x32_bf16 v[8:11], v[158:161], v[210:213], v[8:11]
	v_mfma_f32_16x16x32_bf16 v[60:63], v[154:157], v[190:193], v[60:63]
	v_mfma_f32_16x16x32_bf16 v[56:59], v[162:165], v[190:193], v[56:59]
	v_mfma_f32_16x16x32_bf16 v[44:47], v[154:157], v[198:201], v[44:47]
	v_mfma_f32_16x16x32_bf16 v[40:43], v[162:165], v[198:201], v[40:43]
	v_mfma_f32_16x16x32_bf16 v[28:31], v[154:157], v[206:209], v[28:31]
	v_mfma_f32_16x16x32_bf16 v[24:27], v[162:165], v[206:209], v[24:27]
	v_mfma_f32_16x16x32_bf16 v[12:15], v[154:157], v[214:217], v[12:15]
	v_mfma_f32_16x16x32_bf16 v[8:11], v[162:165], v[214:217], v[8:11]
	s_setprio 0
	s_setprio 1
	v_mfma_f32_16x16x32_bf16 v[52:55], v[166:169], v[186:189], v[52:55]
	v_mfma_f32_16x16x32_bf16 v[48:51], v[174:177], v[186:189], v[48:51]
	v_mfma_f32_16x16x32_bf16 v[36:39], v[166:169], v[194:197], v[36:39]
	v_mfma_f32_16x16x32_bf16 v[32:35], v[174:177], v[194:197], v[32:35]
	v_mfma_f32_16x16x32_bf16 v[20:23], v[166:169], v[202:205], v[20:23]
	v_mfma_f32_16x16x32_bf16 v[16:19], v[174:177], v[202:205], v[16:19]
	v_mfma_f32_16x16x32_bf16 v[4:7], v[166:169], v[210:213], v[4:7]
	v_mfma_f32_16x16x32_bf16 v[0:3], v[174:177], v[210:213], v[0:3]
	v_mfma_f32_16x16x32_bf16 v[52:55], v[170:173], v[190:193], v[52:55]
	v_mfma_f32_16x16x32_bf16 v[48:51], v[178:181], v[190:193], v[48:51]
	v_mfma_f32_16x16x32_bf16 v[36:39], v[170:173], v[198:201], v[36:39]
	v_mfma_f32_16x16x32_bf16 v[32:35], v[178:181], v[198:201], v[32:35]
	v_mfma_f32_16x16x32_bf16 v[20:23], v[170:173], v[206:209], v[20:23]
	v_mfma_f32_16x16x32_bf16 v[16:19], v[178:181], v[206:209], v[16:19]
	v_mfma_f32_16x16x32_bf16 v[4:7], v[170:173], v[214:217], v[4:7]
	v_mfma_f32_16x16x32_bf16 v[0:3], v[178:181], v[214:217], v[0:3]
	s_setprio 0
	s_barrier
	s_add_i32 s62, 0, 0x18000
	s_add_i32 s63, 0, 0x1c000
	v_add_u32_e32 v162, s62, v149
	v_add_u32_e32 v178, s63, v149
	ds_read_b128 v[144:147], v162
	ds_read_b128 v[154:157], v162 offset:1024
	ds_read_b128 v[158:161], v162 offset:2048
	ds_read_b128 v[162:165], v162 offset:3072
	ds_read_b128 v[166:169], v178
	ds_read_b128 v[170:173], v178 offset:1024
	ds_read_b128 v[174:177], v178 offset:2048
	ds_read_b128 v[178:181], v178 offset:3072
	s_add_u32 s46, s46, s16
	s_addc_u32 s47, s47, s17
	s_mov_b32 m0, s3
	s_nop 0
	global_load_lds_dwordx4 v[230:231], off
	s_mov_b32 m0, s28
	s_nop 0
	global_load_lds_dwordx4 v[232:233], off
	s_mov_b32 m0, s33
	v_lshl_add_u64 v[234:235], s[46:47], 0, v[128:129]
	ds_read_b128 v[186:189], v153 offset:32768
	ds_read_b128 v[190:193], v153 offset:33792
	ds_read_b128 v[194:197], v153 offset:34816
	ds_read_b128 v[198:201], v153 offset:35840
	ds_read_b128 v[202:205], v153 offset:36864
	ds_read_b128 v[206:209], v153 offset:37888
	ds_read_b128 v[210:213], v153 offset:38912
	ds_read_b128 v[214:217], v153 offset:39936
	global_load_lds_dwordx4 v[234:235], off
	v_lshl_add_u64 v[234:235], s[46:47], 0, v[132:133]
	s_mov_b32 m0, s48
	s_nop 0
	global_load_lds_dwordx4 v[234:235], off
	s_waitcnt vmcnt(8)
	s_waitcnt lgkmcnt(0)
	s_barrier
	s_setprio 1
	s_waitcnt lgkmcnt(0)
	v_mfma_f32_16x16x32_bf16 v[124:127], v[144:147], v[186:189], v[124:127]
	v_mfma_f32_16x16x32_bf16 v[120:123], v[158:161], v[186:189], v[120:123]
	v_mfma_f32_16x16x32_bf16 v[108:111], v[144:147], v[194:197], v[108:111]
	v_mfma_f32_16x16x32_bf16 v[104:107], v[158:161], v[194:197], v[104:107]
	v_mfma_f32_16x16x32_bf16 v[92:95], v[144:147], v[202:205], v[92:95]
	v_mfma_f32_16x16x32_bf16 v[88:91], v[158:161], v[202:205], v[88:91]
	v_mfma_f32_16x16x32_bf16 v[76:79], v[144:147], v[210:213], v[76:79]
	v_mfma_f32_16x16x32_bf16 v[72:75], v[158:161], v[210:213], v[72:75]
	v_mfma_f32_16x16x32_bf16 v[124:127], v[154:157], v[190:193], v[124:127]
	v_mfma_f32_16x16x32_bf16 v[120:123], v[162:165], v[190:193], v[120:123]
	v_mfma_f32_16x16x32_bf16 v[108:111], v[154:157], v[198:201], v[108:111]
	v_mfma_f32_16x16x32_bf16 v[104:107], v[162:165], v[198:201], v[104:107]
	v_mfma_f32_16x16x32_bf16 v[92:95], v[154:157], v[206:209], v[92:95]
	v_mfma_f32_16x16x32_bf16 v[88:91], v[162:165], v[206:209], v[88:91]
	v_mfma_f32_16x16x32_bf16 v[76:79], v[154:157], v[214:217], v[76:79]
	v_mfma_f32_16x16x32_bf16 v[72:75], v[162:165], v[214:217], v[72:75]
	s_setprio 0
	s_setprio 1
	v_mfma_f32_16x16x32_bf16 v[116:119], v[166:169], v[186:189], v[116:119]
	v_mfma_f32_16x16x32_bf16 v[112:115], v[174:177], v[186:189], v[112:115]
	v_mfma_f32_16x16x32_bf16 v[100:103], v[166:169], v[194:197], v[100:103]
	v_mfma_f32_16x16x32_bf16 v[96:99], v[174:177], v[194:197], v[96:99]
	v_mfma_f32_16x16x32_bf16 v[84:87], v[166:169], v[202:205], v[84:87]
	v_mfma_f32_16x16x32_bf16 v[80:83], v[174:177], v[202:205], v[80:83]
	v_mfma_f32_16x16x32_bf16 v[68:71], v[166:169], v[210:213], v[68:71]
	v_mfma_f32_16x16x32_bf16 v[64:67], v[174:177], v[210:213], v[64:67]
	v_mfma_f32_16x16x32_bf16 v[116:119], v[170:173], v[190:193], v[116:119]
	v_mfma_f32_16x16x32_bf16 v[112:115], v[178:181], v[190:193], v[112:115]
	v_mfma_f32_16x16x32_bf16 v[100:103], v[170:173], v[198:201], v[100:103]
	v_mfma_f32_16x16x32_bf16 v[96:99], v[178:181], v[198:201], v[96:99]
	v_mfma_f32_16x16x32_bf16 v[84:87], v[170:173], v[206:209], v[84:87]
	v_mfma_f32_16x16x32_bf16 v[80:83], v[178:181], v[206:209], v[80:83]
	v_mfma_f32_16x16x32_bf16 v[68:71], v[170:173], v[214:217], v[68:71]
	v_mfma_f32_16x16x32_bf16 v[64:67], v[178:181], v[214:217], v[64:67]
	s_setprio 0
	s_barrier
	s_add_i32 s46, s62, s31
	v_lshl_add_u64 v[182:183], v[182:183], 0, s[40:41]
	s_mov_b32 m0, s46
	ds_read_b128 v[186:189], v153 offset:49152
	ds_read_b128 v[190:193], v153 offset:50176
	ds_read_b128 v[194:197], v153 offset:51200
	ds_read_b128 v[198:201], v153 offset:52224
	ds_read_b128 v[202:205], v153 offset:53248
	ds_read_b128 v[206:209], v153 offset:54272
	ds_read_b128 v[210:213], v153 offset:55296
	ds_read_b128 v[214:217], v153 offset:56320
	global_load_lds_dwordx4 v[182:183], off
	v_lshl_add_u64 v[182:183], v[224:225], 0, s[40:41]
	s_add_i32 m0, s46, 0x2000
	s_add_i32 s46, s63, s31
	global_load_lds_dwordx4 v[182:183], off
	v_lshl_add_u64 v[182:183], v[226:227], 0, s[40:41]
	s_mov_b32 m0, s46
	s_nop 0
	global_load_lds_dwordx4 v[182:183], off
	v_lshl_add_u64 v[182:183], v[228:229], 0, s[40:41]
	s_add_i32 m0, s46, 0x2000
	s_nop 0
	global_load_lds_dwordx4 v[182:183], off
	s_waitcnt vmcnt(6)
	s_waitcnt lgkmcnt(0)
	s_barrier
	s_setprio 1
	s_waitcnt lgkmcnt(0)
	v_mfma_f32_16x16x32_bf16 v[60:63], v[144:147], v[186:189], v[60:63]
	v_mfma_f32_16x16x32_bf16 v[56:59], v[158:161], v[186:189], v[56:59]
	v_mfma_f32_16x16x32_bf16 v[44:47], v[144:147], v[194:197], v[44:47]
	v_mfma_f32_16x16x32_bf16 v[40:43], v[158:161], v[194:197], v[40:43]
	v_mfma_f32_16x16x32_bf16 v[28:31], v[144:147], v[202:205], v[28:31]
	v_mfma_f32_16x16x32_bf16 v[24:27], v[158:161], v[202:205], v[24:27]
	v_mfma_f32_16x16x32_bf16 v[12:15], v[144:147], v[210:213], v[12:15]
	v_mfma_f32_16x16x32_bf16 v[8:11], v[158:161], v[210:213], v[8:11]
	v_mfma_f32_16x16x32_bf16 v[60:63], v[154:157], v[190:193], v[60:63]
	v_mfma_f32_16x16x32_bf16 v[56:59], v[162:165], v[190:193], v[56:59]
	v_mfma_f32_16x16x32_bf16 v[44:47], v[154:157], v[198:201], v[44:47]
	v_mfma_f32_16x16x32_bf16 v[40:43], v[162:165], v[198:201], v[40:43]
	v_mfma_f32_16x16x32_bf16 v[28:31], v[154:157], v[206:209], v[28:31]
	v_mfma_f32_16x16x32_bf16 v[24:27], v[162:165], v[206:209], v[24:27]
	v_mfma_f32_16x16x32_bf16 v[12:15], v[154:157], v[214:217], v[12:15]
	v_mfma_f32_16x16x32_bf16 v[8:11], v[162:165], v[214:217], v[8:11]
	s_setprio 0
	s_setprio 1
	v_mfma_f32_16x16x32_bf16 v[52:55], v[166:169], v[186:189], v[52:55]
	v_mfma_f32_16x16x32_bf16 v[48:51], v[174:177], v[186:189], v[48:51]
	v_mfma_f32_16x16x32_bf16 v[36:39], v[166:169], v[194:197], v[36:39]
	v_mfma_f32_16x16x32_bf16 v[32:35], v[174:177], v[194:197], v[32:35]
	v_mfma_f32_16x16x32_bf16 v[20:23], v[166:169], v[202:205], v[20:23]
	v_mfma_f32_16x16x32_bf16 v[16:19], v[174:177], v[202:205], v[16:19]
	v_mfma_f32_16x16x32_bf16 v[4:7], v[166:169], v[210:213], v[4:7]
	v_mfma_f32_16x16x32_bf16 v[0:3], v[174:177], v[210:213], v[0:3]
	v_mfma_f32_16x16x32_bf16 v[52:55], v[170:173], v[190:193], v[52:55]
	v_mfma_f32_16x16x32_bf16 v[48:51], v[178:181], v[190:193], v[48:51]
	v_mfma_f32_16x16x32_bf16 v[36:39], v[170:173], v[198:201], v[36:39]
	v_mfma_f32_16x16x32_bf16 v[32:35], v[178:181], v[198:201], v[32:35]
	v_mfma_f32_16x16x32_bf16 v[20:23], v[170:173], v[206:209], v[20:23]
	v_mfma_f32_16x16x32_bf16 v[16:19], v[178:181], v[206:209], v[16:19]
	v_mfma_f32_16x16x32_bf16 v[4:7], v[170:173], v[214:217], v[4:7]
	v_mfma_f32_16x16x32_bf16 v[0:3], v[178:181], v[214:217], v[0:3]
	s_setprio 0
	s_barrier
	s_add_u32 s44, s44, 0x100
	s_addc_u32 s45, s45, 0
	s_add_u32 s59, s59, 0x100
	s_addc_u32 s60, s60, 0
	s_cmp_ge_i32 s61, s51
	s_mov_b32 s46, s61
	s_cbranch_scc0 .LBB0_1003
	s_branch .LBB0_1004

.LBB0_1004:
	v_lshl_add_u32 v146, s58, 8, v148
	v_lshl_add_u32 v144, s36, 8, v150
	v_lshlrev_b32_e32 v144, 1, v144
	v_lshl_add_u32 v162, v146, 11, v144
	global_load_dwordx4 v[186:189], v162, s[34:35]
	global_load_dwordx4 v[190:193], v162, s[34:35] offset:256
	v_add_u32_e32 v163, 0x8000, v162
	global_load_dwordx4 v[194:197], v163, s[34:35]
	global_load_dwordx4 v[198:201], v163, s[34:35] offset:256
	v_add_u32_e32 v163, 0x10000, v162
	global_load_dwordx4 v[202:205], v163, s[34:35]
	global_load_dwordx4 v[206:209], v163, s[34:35] offset:256
	v_add_u32_e32 v163, 0x18000, v162
	global_load_dwordx4 v[210:213], v163, s[34:35]
	global_load_dwordx4 v[214:217], v163, s[34:35] offset:256
	v_add_u32_e32 v163, 0x40000, v162
	global_load_dwordx4 v[224:227], v163, s[34:35]
	global_load_dwordx4 v[236:239], v163, s[34:35] offset:256
	v_add_u32_e32 v163, 0x48000, v162
	global_load_dwordx4 v[240:243], v163, s[34:35]
	global_load_dwordx4 v[244:247], v163, s[34:35] offset:256
	v_add_u32_e32 v163, 0x50000, v162
	global_load_dwordx4 v[154:157], v163, s[34:35]
	global_load_dwordx4 v[158:161], v163, s[34:35] offset:256
	v_add_u32_e32 v163, 0x58000, v162
	global_load_dwordx4 v[164:167], v163, s[34:35]
	global_load_dwordx4 v[250:253], v163, s[34:35] offset:256
	s_and_b64 vcc, exec, s[94:95]
	s_cbranch_vccz .LBB0_1006
	s_barrier
.LBB0_1006:
	s_lshl_b32 s44, s36, 2
	s_add_u32 s44, s44, s29
	s_lshl_b32 s44, s44, 2
	v_lshl_add_u32 v170, v146, 6, s44
	v_add_u32_e32 v171, 0x2000, v170
	s_waitcnt vmcnt(14)
	v_lshlrev_b32_e32 v172, 16, v186
	v_and_b32_e32 v173, 0xffff0000, v186
	v_lshlrev_b32_e32 v186, 16, v187
	v_and_b32_e32 v187, 0xffff0000, v187
	v_lshlrev_b32_e32 v174, 16, v188
	v_and_b32_e32 v175, 0xffff0000, v188
	v_lshlrev_b32_e32 v188, 16, v189
	v_and_b32_e32 v189, 0xffff0000, v189
	v_pk_add_f32 v[126:127], v[126:127], v[186:187]
	v_pk_add_f32 v[124:125], v[124:125], v[172:173]
	v_pk_add_f32 v[122:123], v[122:123], v[188:189]
	v_pk_add_f32 v[120:121], v[120:121], v[174:175]
	v_lshlrev_b32_e32 v176, 16, v190
	v_and_b32_e32 v177, 0xffff0000, v190
	v_lshlrev_b32_e32 v190, 16, v191
	v_and_b32_e32 v191, 0xffff0000, v191
	v_lshlrev_b32_e32 v178, 16, v192
	v_and_b32_e32 v179, 0xffff0000, v192
	v_lshlrev_b32_e32 v192, 16, v193
	v_and_b32_e32 v193, 0xffff0000, v193
	v_pk_add_f32 v[118:119], v[118:119], v[190:191]
	v_pk_add_f32 v[116:117], v[116:117], v[176:177]
	v_pk_add_f32 v[114:115], v[114:115], v[192:193]
	v_pk_add_f32 v[112:113], v[112:113], v[178:179]
	v_mul_f32_e32 v180, v125, v125
	v_mul_f32_e32 v181, v127, v127
	v_mul_f32_e32 v182, v121, v121
	v_mul_f32_e32 v183, v123, v123
	v_fmac_f32_e32 v180, v124, v124
	v_fmac_f32_e32 v181, v126, v126
	v_fmac_f32_e32 v182, v120, v120
	v_fmac_f32_e32 v183, v122, v122
	v_add_f32_e32 v180, v180, v181
	v_add_f32_e32 v182, v182, v183
	v_add_f32_e32 v180, v180, v182
	v_mul_f32_e32 v147, v117, v117
	v_mul_f32_e32 v181, v119, v119
	v_mul_f32_e32 v182, v113, v113
	v_mul_f32_e32 v183, v115, v115
	v_fmac_f32_e32 v147, v116, v116
	v_fmac_f32_e32 v181, v118, v118
	v_fmac_f32_e32 v182, v112, v112
	v_fmac_f32_e32 v183, v114, v114
	v_add_f32_e32 v147, v147, v181
	v_add_f32_e32 v182, v182, v183
	v_add_f32_e32 v147, v147, v182
	v_add_f32_e32 v147, v180, v147
	ds_bpermute_b32 v145, v222, v147
	v_cvt_pk_bf16_f32 v124, v124, v125
	v_cvt_pk_bf16_f32 v125, v126, v127
	v_cvt_pk_bf16_f32 v126, v120, v121
	v_cvt_pk_bf16_f32 v127, v122, v123
	global_store_dwordx4 v162, v[124:127], s[34:35]
	s_waitcnt lgkmcnt(0)
	v_add_f32_e32 v147, v147, v145
	ds_bpermute_b32 v145, v223, v147
	v_cvt_pk_bf16_f32 v116, v116, v117
	v_cvt_pk_bf16_f32 v117, v118, v119
	v_cvt_pk_bf16_f32 v118, v112, v113
	v_cvt_pk_bf16_f32 v119, v114, v115
	global_store_dwordx4 v162, v[116:119], s[34:35] offset:256
	s_waitcnt lgkmcnt(0)
	v_add_f32_e32 v147, v147, v145
	s_and_saveexec_b64 s[46:47], s[10:11]
	global_store_dword v170, v147, s[38:39] offset:0
	s_mov_b64 exec, s[46:47]
	s_waitcnt vmcnt(15)
	v_add_u32_e32 v163, 0x8000, v162
	v_lshlrev_b32_e32 v172, 16, v194
	v_and_b32_e32 v173, 0xffff0000, v194
	v_lshlrev_b32_e32 v194, 16, v195
	v_and_b32_e32 v195, 0xffff0000, v195
	v_lshlrev_b32_e32 v174, 16, v196
	v_and_b32_e32 v175, 0xffff0000, v196
	v_lshlrev_b32_e32 v196, 16, v197
	v_and_b32_e32 v197, 0xffff0000, v197
	v_pk_add_f32 v[110:111], v[110:111], v[194:195]
	v_pk_add_f32 v[108:109], v[108:109], v[172:173]
	v_pk_add_f32 v[106:107], v[106:107], v[196:197]
	v_pk_add_f32 v[104:105], v[104:105], v[174:175]
	v_lshlrev_b32_e32 v176, 16, v198
	v_and_b32_e32 v177, 0xffff0000, v198
	v_lshlrev_b32_e32 v198, 16, v199
	v_and_b32_e32 v199, 0xffff0000, v199
	v_lshlrev_b32_e32 v178, 16, v200
	v_and_b32_e32 v179, 0xffff0000, v200
	v_lshlrev_b32_e32 v200, 16, v201
	v_and_b32_e32 v201, 0xffff0000, v201
	v_pk_add_f32 v[102:103], v[102:103], v[198:199]
	v_pk_add_f32 v[100:101], v[100:101], v[176:177]
	v_pk_add_f32 v[98:99], v[98:99], v[200:201]
	v_pk_add_f32 v[96:97], v[96:97], v[178:179]
	v_mul_f32_e32 v180, v109, v109
	v_mul_f32_e32 v181, v111, v111
	v_mul_f32_e32 v182, v105, v105
	v_mul_f32_e32 v183, v107, v107
	v_fmac_f32_e32 v180, v108, v108
	v_fmac_f32_e32 v181, v110, v110
	v_fmac_f32_e32 v182, v104, v104
	v_fmac_f32_e32 v183, v106, v106
	v_add_f32_e32 v180, v180, v181
	v_add_f32_e32 v182, v182, v183
	v_add_f32_e32 v180, v180, v182
	v_mul_f32_e32 v147, v101, v101
	v_mul_f32_e32 v181, v103, v103
	v_mul_f32_e32 v182, v97, v97
	v_mul_f32_e32 v183, v99, v99
	v_fmac_f32_e32 v147, v100, v100
	v_fmac_f32_e32 v181, v102, v102
	v_fmac_f32_e32 v182, v96, v96
	v_fmac_f32_e32 v183, v98, v98
	v_add_f32_e32 v147, v147, v181
	v_add_f32_e32 v182, v182, v183
	v_add_f32_e32 v147, v147, v182
	v_add_f32_e32 v147, v180, v147
	ds_bpermute_b32 v145, v222, v147
	v_cvt_pk_bf16_f32 v108, v108, v109
	v_cvt_pk_bf16_f32 v109, v110, v111
	v_cvt_pk_bf16_f32 v110, v104, v105
	v_cvt_pk_bf16_f32 v111, v106, v107
	global_store_dwordx4 v163, v[108:111], s[34:35]
	s_waitcnt lgkmcnt(0)
	v_add_f32_e32 v147, v147, v145
	ds_bpermute_b32 v145, v223, v147
	v_cvt_pk_bf16_f32 v100, v100, v101
	v_cvt_pk_bf16_f32 v101, v102, v103
	v_cvt_pk_bf16_f32 v102, v96, v97
	v_cvt_pk_bf16_f32 v103, v98, v99
	global_store_dwordx4 v163, v[100:103], s[34:35] offset:256
	s_waitcnt lgkmcnt(0)
	v_add_f32_e32 v147, v147, v145
	s_and_saveexec_b64 s[46:47], s[10:11]
	global_store_dword v170, v147, s[38:39] offset:1024
	s_mov_b64 exec, s[46:47]
	s_waitcnt vmcnt(16)
	v_add_u32_e32 v163, 0x10000, v162
	v_lshlrev_b32_e32 v172, 16, v202
	v_and_b32_e32 v173, 0xffff0000, v202
	v_lshlrev_b32_e32 v202, 16, v203
	v_and_b32_e32 v203, 0xffff0000, v203
	v_lshlrev_b32_e32 v174, 16, v204
	v_and_b32_e32 v175, 0xffff0000, v204
	v_lshlrev_b32_e32 v204, 16, v205
	v_and_b32_e32 v205, 0xffff0000, v205
	v_pk_add_f32 v[94:95], v[94:95], v[202:203]
	v_pk_add_f32 v[92:93], v[92:93], v[172:173]
	v_pk_add_f32 v[90:91], v[90:91], v[204:205]
	v_pk_add_f32 v[88:89], v[88:89], v[174:175]
	v_lshlrev_b32_e32 v176, 16, v206
	v_and_b32_e32 v177, 0xffff0000, v206
	v_lshlrev_b32_e32 v206, 16, v207
	v_and_b32_e32 v207, 0xffff0000, v207
	v_lshlrev_b32_e32 v178, 16, v208
	v_and_b32_e32 v179, 0xffff0000, v208
	v_lshlrev_b32_e32 v208, 16, v209
	v_and_b32_e32 v209, 0xffff0000, v209
	v_pk_add_f32 v[86:87], v[86:87], v[206:207]
	v_pk_add_f32 v[84:85], v[84:85], v[176:177]
	v_pk_add_f32 v[82:83], v[82:83], v[208:209]
	v_pk_add_f32 v[80:81], v[80:81], v[178:179]
	v_mul_f32_e32 v180, v93, v93
	v_mul_f32_e32 v181, v95, v95
	v_mul_f32_e32 v182, v89, v89
	v_mul_f32_e32 v183, v91, v91
	v_fmac_f32_e32 v180, v92, v92
	v_fmac_f32_e32 v181, v94, v94
	v_fmac_f32_e32 v182, v88, v88
	v_fmac_f32_e32 v183, v90, v90
	v_add_f32_e32 v180, v180, v181
	v_add_f32_e32 v182, v182, v183
	v_add_f32_e32 v180, v180, v182
	v_mul_f32_e32 v147, v85, v85
	v_mul_f32_e32 v181, v87, v87
	v_mul_f32_e32 v182, v81, v81
	v_mul_f32_e32 v183, v83, v83
	v_fmac_f32_e32 v147, v84, v84
	v_fmac_f32_e32 v181, v86, v86
	v_fmac_f32_e32 v182, v80, v80
	v_fmac_f32_e32 v183, v82, v82
	v_add_f32_e32 v147, v147, v181
	v_add_f32_e32 v182, v182, v183
	v_add_f32_e32 v147, v147, v182
	v_add_f32_e32 v147, v180, v147
	ds_bpermute_b32 v145, v222, v147
	v_cvt_pk_bf16_f32 v92, v92, v93
	v_cvt_pk_bf16_f32 v93, v94, v95
	v_cvt_pk_bf16_f32 v94, v88, v89
	v_cvt_pk_bf16_f32 v95, v90, v91
	global_store_dwordx4 v163, v[92:95], s[34:35]
	s_waitcnt lgkmcnt(0)
	v_add_f32_e32 v147, v147, v145
	ds_bpermute_b32 v145, v223, v147
	v_cvt_pk_bf16_f32 v84, v84, v85
	v_cvt_pk_bf16_f32 v85, v86, v87
	v_cvt_pk_bf16_f32 v86, v80, v81
	v_cvt_pk_bf16_f32 v87, v82, v83
	global_store_dwordx4 v163, v[84:87], s[34:35] offset:256
	s_waitcnt lgkmcnt(0)
	v_add_f32_e32 v147, v147, v145
	s_and_saveexec_b64 s[46:47], s[10:11]
	global_store_dword v170, v147, s[38:39] offset:2048
	s_mov_b64 exec, s[46:47]
	s_waitcnt vmcnt(17)
	v_add_u32_e32 v163, 0x18000, v162
	v_lshlrev_b32_e32 v172, 16, v210
	v_and_b32_e32 v173, 0xffff0000, v210
	v_lshlrev_b32_e32 v210, 16, v211
	v_and_b32_e32 v211, 0xffff0000, v211
	v_lshlrev_b32_e32 v174, 16, v212
	v_and_b32_e32 v175, 0xffff0000, v212
	v_lshlrev_b32_e32 v212, 16, v213
	v_and_b32_e32 v213, 0xffff0000, v213
	v_pk_add_f32 v[78:79], v[78:79], v[210:211]
	v_pk_add_f32 v[76:77], v[76:77], v[172:173]
	v_pk_add_f32 v[74:75], v[74:75], v[212:213]
	v_pk_add_f32 v[72:73], v[72:73], v[174:175]
	v_lshlrev_b32_e32 v176, 16, v214
	v_and_b32_e32 v177, 0xffff0000, v214
	v_lshlrev_b32_e32 v214, 16, v215
	v_and_b32_e32 v215, 0xffff0000, v215
	v_lshlrev_b32_e32 v178, 16, v216
	v_and_b32_e32 v179, 0xffff0000, v216
	v_lshlrev_b32_e32 v216, 16, v217
	v_and_b32_e32 v217, 0xffff0000, v217
	v_pk_add_f32 v[70:71], v[70:71], v[214:215]
	v_pk_add_f32 v[68:69], v[68:69], v[176:177]
	v_pk_add_f32 v[66:67], v[66:67], v[216:217]
	v_pk_add_f32 v[64:65], v[64:65], v[178:179]
	v_mul_f32_e32 v180, v77, v77
	v_mul_f32_e32 v181, v79, v79
	v_mul_f32_e32 v182, v73, v73
	v_mul_f32_e32 v183, v75, v75
	v_fmac_f32_e32 v180, v76, v76
	v_fmac_f32_e32 v181, v78, v78
	v_fmac_f32_e32 v182, v72, v72
	v_fmac_f32_e32 v183, v74, v74
	v_add_f32_e32 v180, v180, v181
	v_add_f32_e32 v182, v182, v183
	v_add_f32_e32 v180, v180, v182
	v_mul_f32_e32 v147, v69, v69
	v_mul_f32_e32 v181, v71, v71
	v_mul_f32_e32 v182, v65, v65
	v_mul_f32_e32 v183, v67, v67
	v_fmac_f32_e32 v147, v68, v68
	v_fmac_f32_e32 v181, v70, v70
	v_fmac_f32_e32 v182, v64, v64
	v_fmac_f32_e32 v183, v66, v66
	v_add_f32_e32 v147, v147, v181
	v_add_f32_e32 v182, v182, v183
	v_add_f32_e32 v147, v147, v182
	v_add_f32_e32 v147, v180, v147
	ds_bpermute_b32 v145, v222, v147
	v_cvt_pk_bf16_f32 v76, v76, v77
	v_cvt_pk_bf16_f32 v77, v78, v79
	v_cvt_pk_bf16_f32 v78, v72, v73
	v_cvt_pk_bf16_f32 v79, v74, v75
	global_store_dwordx4 v163, v[76:79], s[34:35]
	s_waitcnt lgkmcnt(0)
	v_add_f32_e32 v147, v147, v145
	ds_bpermute_b32 v145, v223, v147
	v_cvt_pk_bf16_f32 v68, v68, v69
	v_cvt_pk_bf16_f32 v69, v70, v71
	v_cvt_pk_bf16_f32 v70, v64, v65
	v_cvt_pk_bf16_f32 v71, v66, v67
	global_store_dwordx4 v163, v[68:71], s[34:35] offset:256
	s_waitcnt lgkmcnt(0)
	v_add_f32_e32 v147, v147, v145
	s_and_saveexec_b64 s[46:47], s[10:11]
	global_store_dword v170, v147, s[38:39] offset:3072
	s_mov_b64 exec, s[46:47]
	s_waitcnt vmcnt(18)
	v_add_u32_e32 v163, 0x40000, v162
	v_lshlrev_b32_e32 v172, 16, v224
	v_and_b32_e32 v173, 0xffff0000, v224
	v_lshlrev_b32_e32 v224, 16, v225
	v_and_b32_e32 v225, 0xffff0000, v225
	v_lshlrev_b32_e32 v174, 16, v226
	v_and_b32_e32 v175, 0xffff0000, v226
	v_lshlrev_b32_e32 v226, 16, v227
	v_and_b32_e32 v227, 0xffff0000, v227
	v_pk_add_f32 v[62:63], v[62:63], v[224:225]
	v_pk_add_f32 v[60:61], v[60:61], v[172:173]
	v_pk_add_f32 v[58:59], v[58:59], v[226:227]
	v_pk_add_f32 v[56:57], v[56:57], v[174:175]
	v_lshlrev_b32_e32 v176, 16, v236
	v_and_b32_e32 v177, 0xffff0000, v236
	v_lshlrev_b32_e32 v236, 16, v237
	v_and_b32_e32 v237, 0xffff0000, v237
	v_lshlrev_b32_e32 v178, 16, v238
	v_and_b32_e32 v179, 0xffff0000, v238
	v_lshlrev_b32_e32 v238, 16, v239
	v_and_b32_e32 v239, 0xffff0000, v239
	v_pk_add_f32 v[54:55], v[54:55], v[236:237]
	v_pk_add_f32 v[52:53], v[52:53], v[176:177]
	v_pk_add_f32 v[50:51], v[50:51], v[238:239]
	v_pk_add_f32 v[48:49], v[48:49], v[178:179]
	v_mul_f32_e32 v180, v61, v61
	v_mul_f32_e32 v181, v63, v63
	v_mul_f32_e32 v182, v57, v57
	v_mul_f32_e32 v183, v59, v59
	v_fmac_f32_e32 v180, v60, v60
	v_fmac_f32_e32 v181, v62, v62
	v_fmac_f32_e32 v182, v56, v56
	v_fmac_f32_e32 v183, v58, v58
	v_add_f32_e32 v180, v180, v181
	v_add_f32_e32 v182, v182, v183
	v_add_f32_e32 v180, v180, v182
	v_mul_f32_e32 v147, v53, v53
	v_mul_f32_e32 v181, v55, v55
	v_mul_f32_e32 v182, v49, v49
	v_mul_f32_e32 v183, v51, v51
	v_fmac_f32_e32 v147, v52, v52
	v_fmac_f32_e32 v181, v54, v54
	v_fmac_f32_e32 v182, v48, v48
	v_fmac_f32_e32 v183, v50, v50
	v_add_f32_e32 v147, v147, v181
	v_add_f32_e32 v182, v182, v183
	v_add_f32_e32 v147, v147, v182
	v_add_f32_e32 v147, v180, v147
	ds_bpermute_b32 v145, v222, v147
	v_cvt_pk_bf16_f32 v60, v60, v61
	v_cvt_pk_bf16_f32 v61, v62, v63
	v_cvt_pk_bf16_f32 v62, v56, v57
	v_cvt_pk_bf16_f32 v63, v58, v59
	global_store_dwordx4 v163, v[60:63], s[34:35]
	s_waitcnt lgkmcnt(0)
	v_add_f32_e32 v147, v147, v145
	ds_bpermute_b32 v145, v223, v147
	v_cvt_pk_bf16_f32 v52, v52, v53
	v_cvt_pk_bf16_f32 v53, v54, v55
	v_cvt_pk_bf16_f32 v54, v48, v49
	v_cvt_pk_bf16_f32 v55, v50, v51
	global_store_dwordx4 v163, v[52:55], s[34:35] offset:256
	s_waitcnt lgkmcnt(0)
	v_add_f32_e32 v147, v147, v145
	s_and_saveexec_b64 s[46:47], s[10:11]
	global_store_dword v171, v147, s[38:39] offset:0
	s_mov_b64 exec, s[46:47]
	s_waitcnt vmcnt(19)
	v_add_u32_e32 v163, 0x48000, v162
	v_lshlrev_b32_e32 v172, 16, v240
	v_and_b32_e32 v173, 0xffff0000, v240
	v_lshlrev_b32_e32 v240, 16, v241
	v_and_b32_e32 v241, 0xffff0000, v241
	v_lshlrev_b32_e32 v174, 16, v242
	v_and_b32_e32 v175, 0xffff0000, v242
	v_lshlrev_b32_e32 v242, 16, v243
	v_and_b32_e32 v243, 0xffff0000, v243
	v_pk_add_f32 v[46:47], v[46:47], v[240:241]
	v_pk_add_f32 v[44:45], v[44:45], v[172:173]
	v_pk_add_f32 v[42:43], v[42:43], v[242:243]
	v_pk_add_f32 v[40:41], v[40:41], v[174:175]
	v_lshlrev_b32_e32 v176, 16, v244
	v_and_b32_e32 v177, 0xffff0000, v244
	v_lshlrev_b32_e32 v244, 16, v245
	v_and_b32_e32 v245, 0xffff0000, v245
	v_lshlrev_b32_e32 v178, 16, v246
	v_and_b32_e32 v179, 0xffff0000, v246
	v_lshlrev_b32_e32 v246, 16, v247
	v_and_b32_e32 v247, 0xffff0000, v247
	v_pk_add_f32 v[38:39], v[38:39], v[244:245]
	v_pk_add_f32 v[36:37], v[36:37], v[176:177]
	v_pk_add_f32 v[34:35], v[34:35], v[246:247]
	v_pk_add_f32 v[32:33], v[32:33], v[178:179]
	v_mul_f32_e32 v180, v45, v45
	v_mul_f32_e32 v181, v47, v47
	v_mul_f32_e32 v182, v41, v41
	v_mul_f32_e32 v183, v43, v43
	v_fmac_f32_e32 v180, v44, v44
	v_fmac_f32_e32 v181, v46, v46
	v_fmac_f32_e32 v182, v40, v40
	v_fmac_f32_e32 v183, v42, v42
	v_add_f32_e32 v180, v180, v181
	v_add_f32_e32 v182, v182, v183
	v_add_f32_e32 v180, v180, v182
	v_mul_f32_e32 v147, v37, v37
	v_mul_f32_e32 v181, v39, v39
	v_mul_f32_e32 v182, v33, v33
	v_mul_f32_e32 v183, v35, v35
	v_fmac_f32_e32 v147, v36, v36
	v_fmac_f32_e32 v181, v38, v38
	v_fmac_f32_e32 v182, v32, v32
	v_fmac_f32_e32 v183, v34, v34
	v_add_f32_e32 v147, v147, v181
	v_add_f32_e32 v182, v182, v183
	v_add_f32_e32 v147, v147, v182
	v_add_f32_e32 v147, v180, v147
	ds_bpermute_b32 v145, v222, v147
	v_cvt_pk_bf16_f32 v44, v44, v45
	v_cvt_pk_bf16_f32 v45, v46, v47
	v_cvt_pk_bf16_f32 v46, v40, v41
	v_cvt_pk_bf16_f32 v47, v42, v43
	global_store_dwordx4 v163, v[44:47], s[34:35]
	s_waitcnt lgkmcnt(0)
	v_add_f32_e32 v147, v147, v145
	ds_bpermute_b32 v145, v223, v147
	v_cvt_pk_bf16_f32 v36, v36, v37
	v_cvt_pk_bf16_f32 v37, v38, v39
	v_cvt_pk_bf16_f32 v38, v32, v33
	v_cvt_pk_bf16_f32 v39, v34, v35
	global_store_dwordx4 v163, v[36:39], s[34:35] offset:256
	s_waitcnt lgkmcnt(0)
	v_add_f32_e32 v147, v147, v145
	s_and_saveexec_b64 s[46:47], s[10:11]
	global_store_dword v171, v147, s[38:39] offset:1024
	s_mov_b64 exec, s[46:47]
	s_waitcnt vmcnt(20)
	v_add_u32_e32 v163, 0x50000, v162
	v_lshlrev_b32_e32 v172, 16, v154
	v_and_b32_e32 v173, 0xffff0000, v154
	v_lshlrev_b32_e32 v154, 16, v155
	v_and_b32_e32 v155, 0xffff0000, v155
	v_lshlrev_b32_e32 v174, 16, v156
	v_and_b32_e32 v175, 0xffff0000, v156
	v_lshlrev_b32_e32 v156, 16, v157
	v_and_b32_e32 v157, 0xffff0000, v157
	v_pk_add_f32 v[30:31], v[30:31], v[154:155]
	v_pk_add_f32 v[28:29], v[28:29], v[172:173]
	v_pk_add_f32 v[26:27], v[26:27], v[156:157]
	v_pk_add_f32 v[24:25], v[24:25], v[174:175]
	v_lshlrev_b32_e32 v176, 16, v158
	v_and_b32_e32 v177, 0xffff0000, v158
	v_lshlrev_b32_e32 v158, 16, v159
	v_and_b32_e32 v159, 0xffff0000, v159
	v_lshlrev_b32_e32 v178, 16, v160
	v_and_b32_e32 v179, 0xffff0000, v160
	v_lshlrev_b32_e32 v160, 16, v161
	v_and_b32_e32 v161, 0xffff0000, v161
	v_pk_add_f32 v[22:23], v[22:23], v[158:159]
	v_pk_add_f32 v[20:21], v[20:21], v[176:177]
	v_pk_add_f32 v[18:19], v[18:19], v[160:161]
	v_pk_add_f32 v[16:17], v[16:17], v[178:179]
	v_mul_f32_e32 v180, v29, v29
	v_mul_f32_e32 v181, v31, v31
	v_mul_f32_e32 v182, v25, v25
	v_mul_f32_e32 v183, v27, v27
	v_fmac_f32_e32 v180, v28, v28
	v_fmac_f32_e32 v181, v30, v30
	v_fmac_f32_e32 v182, v24, v24
	v_fmac_f32_e32 v183, v26, v26
	v_add_f32_e32 v180, v180, v181
	v_add_f32_e32 v182, v182, v183
	v_add_f32_e32 v180, v180, v182
	v_mul_f32_e32 v147, v21, v21
	v_mul_f32_e32 v181, v23, v23
	v_mul_f32_e32 v182, v17, v17
	v_mul_f32_e32 v183, v19, v19
	v_fmac_f32_e32 v147, v20, v20
	v_fmac_f32_e32 v181, v22, v22
	v_fmac_f32_e32 v182, v16, v16
	v_fmac_f32_e32 v183, v18, v18
	v_add_f32_e32 v147, v147, v181
	v_add_f32_e32 v182, v182, v183
	v_add_f32_e32 v147, v147, v182
	v_add_f32_e32 v147, v180, v147
	ds_bpermute_b32 v145, v222, v147
	v_cvt_pk_bf16_f32 v28, v28, v29
	v_cvt_pk_bf16_f32 v29, v30, v31
	v_cvt_pk_bf16_f32 v30, v24, v25
	v_cvt_pk_bf16_f32 v31, v26, v27
	global_store_dwordx4 v163, v[28:31], s[34:35]
	s_waitcnt lgkmcnt(0)
	v_add_f32_e32 v147, v147, v145
	ds_bpermute_b32 v145, v223, v147
	v_cvt_pk_bf16_f32 v20, v20, v21
	v_cvt_pk_bf16_f32 v21, v22, v23
	v_cvt_pk_bf16_f32 v22, v16, v17
	v_cvt_pk_bf16_f32 v23, v18, v19
	global_store_dwordx4 v163, v[20:23], s[34:35] offset:256
	s_waitcnt lgkmcnt(0)
	v_add_f32_e32 v147, v147, v145
	s_and_saveexec_b64 s[46:47], s[10:11]
	global_store_dword v171, v147, s[38:39] offset:2048
	s_mov_b64 exec, s[46:47]
	s_waitcnt vmcnt(21)
	v_add_u32_e32 v163, 0x58000, v162
	v_lshlrev_b32_e32 v172, 16, v164
	v_and_b32_e32 v173, 0xffff0000, v164
	v_lshlrev_b32_e32 v164, 16, v165
	v_and_b32_e32 v165, 0xffff0000, v165
	v_lshlrev_b32_e32 v174, 16, v166
	v_and_b32_e32 v175, 0xffff0000, v166
	v_lshlrev_b32_e32 v166, 16, v167
	v_and_b32_e32 v167, 0xffff0000, v167
	v_pk_add_f32 v[14:15], v[14:15], v[164:165]
	v_pk_add_f32 v[12:13], v[12:13], v[172:173]
	v_pk_add_f32 v[10:11], v[10:11], v[166:167]
	v_pk_add_f32 v[8:9], v[8:9], v[174:175]
	v_lshlrev_b32_e32 v176, 16, v250
	v_and_b32_e32 v177, 0xffff0000, v250
	v_lshlrev_b32_e32 v250, 16, v251
	v_and_b32_e32 v251, 0xffff0000, v251
	v_lshlrev_b32_e32 v178, 16, v252
	v_and_b32_e32 v179, 0xffff0000, v252
	v_lshlrev_b32_e32 v252, 16, v253
	v_and_b32_e32 v253, 0xffff0000, v253
	v_pk_add_f32 v[6:7], v[6:7], v[250:251]
	v_pk_add_f32 v[4:5], v[4:5], v[176:177]
	v_pk_add_f32 v[2:3], v[2:3], v[252:253]
	v_pk_add_f32 v[0:1], v[0:1], v[178:179]
	v_mul_f32_e32 v180, v13, v13
	v_mul_f32_e32 v181, v15, v15
	v_mul_f32_e32 v182, v9, v9
	v_mul_f32_e32 v183, v11, v11
	v_fmac_f32_e32 v180, v12, v12
	v_fmac_f32_e32 v181, v14, v14
	v_fmac_f32_e32 v182, v8, v8
	v_fmac_f32_e32 v183, v10, v10
	v_add_f32_e32 v180, v180, v181
	v_add_f32_e32 v182, v182, v183
	v_add_f32_e32 v180, v180, v182
	v_mul_f32_e32 v147, v5, v5
	v_mul_f32_e32 v181, v7, v7
	v_mul_f32_e32 v182, v1, v1
	v_mul_f32_e32 v183, v3, v3
	v_fmac_f32_e32 v147, v4, v4
	v_fmac_f32_e32 v181, v6, v6
	v_fmac_f32_e32 v182, v0, v0
	v_fmac_f32_e32 v183, v2, v2
	v_add_f32_e32 v147, v147, v181
	v_add_f32_e32 v182, v182, v183
	v_add_f32_e32 v147, v147, v182
	v_add_f32_e32 v147, v180, v147
	ds_bpermute_b32 v145, v222, v147
	v_cvt_pk_bf16_f32 v12, v12, v13
	v_cvt_pk_bf16_f32 v13, v14, v15
	v_cvt_pk_bf16_f32 v14, v8, v9
	v_cvt_pk_bf16_f32 v15, v10, v11
	global_store_dwordx4 v163, v[12:15], s[34:35]
	s_waitcnt lgkmcnt(0)
	v_add_f32_e32 v147, v147, v145
	ds_bpermute_b32 v145, v223, v147
	v_cvt_pk_bf16_f32 v4, v4, v5
	v_cvt_pk_bf16_f32 v5, v6, v7
	v_cvt_pk_bf16_f32 v6, v0, v1
	v_cvt_pk_bf16_f32 v7, v2, v3
	global_store_dwordx4 v163, v[4:7], s[34:35] offset:256
	s_waitcnt lgkmcnt(0)
	v_add_f32_e32 v147, v147, v145
	s_and_saveexec_b64 s[46:47], s[10:11]
	global_store_dword v171, v147, s[38:39] offset:3072
